# on top of v7: HGRN2 output phase run-entry state reconstruction: the 16 loads per earlier run are issued together (6 pairs in flight, 2 reissued) with counted waits instead of a full wait after every
# baseline (speedup 1.0000x reference)
; #define GAS __attribute__((address_space(1)))
; __device__ __forceinline__ void hgrn_r3(const GAS bf16* proj, const GAS float* RU, const GAS float* RD, GAS bf16* y, int TOKG, const GAS float* ogain, unsigned char* lds, int tid, int lane, int wave, int bid, int G) {
;     ...
;         for (int r2 = 0; r2 < rr; ++r2) { const int rn = run - rr + r2;
;             const GAS float* up = RU + (size_t)rn * 16384 + (16 * wave + fr) * 128 + 4 * fq; const GAS float* dp = RD + (size_t)rn * 128 + 4 * fq;
; #pragma unroll
;             for (int nk = 0; nk < 8; ++nk) { const f32x4h uu = *(const GAS f32x4h*)(up + 16 * nk), dd = *(const GAS f32x4h*)(dp + 16 * nk); Sm[nk] = Sm[nk] * dd + uu; } }
.LBB0_380:
	s_add_i32 s78, s54, s60
	s_ashr_i32 s79, s78, 31
	s_lshl_b64 s[80:81], s[78:79], 16
	v_lshl_add_u64 v[44:45], v[86:87], 0, s[80:81]
	s_lshl_b64 s[78:79], s[78:79], 9
	v_lshl_add_u64 v[46:47], v[88:89], 0, s[78:79]
	global_load_dwordx4 v[36:39], v[44:45], off
	global_load_dwordx4 v[40:43], v[46:47], off
	global_load_dwordx4 v[136:139], v[44:45], off offset:64
	global_load_dwordx4 v[140:143], v[46:47], off offset:64
	global_load_dwordx4 v[144:147], v[44:45], off offset:128
	global_load_dwordx4 v[148:151], v[46:47], off offset:128
	global_load_dwordx4 v[152:155], v[44:45], off offset:192
	global_load_dwordx4 v[214:217], v[46:47], off offset:192
	global_load_dwordx4 v[218:221], v[44:45], off offset:256
	global_load_dwordx4 v[222:225], v[46:47], off offset:256
	global_load_dwordx4 v[226:229], v[44:45], off offset:320
	global_load_dwordx4 v[230:233], v[46:47], off offset:320
	s_add_i32 s60, s60, 1
	s_cmp_ge_i32 s60, s55
	s_waitcnt vmcnt(10)
	v_pk_fma_f32 v[22:23], v[22:23], v[42:43], v[38:39]
	v_pk_fma_f32 v[20:21], v[20:21], v[40:41], v[36:37]
	global_load_dwordx4 v[36:39], v[44:45], off offset:384
	global_load_dwordx4 v[40:43], v[46:47], off offset:384
	s_waitcnt vmcnt(10)
	v_pk_fma_f32 v[6:7], v[6:7], v[142:143], v[138:139]
	v_pk_fma_f32 v[4:5], v[4:5], v[140:141], v[136:137]
	global_load_dwordx4 v[136:139], v[44:45], off offset:448
	global_load_dwordx4 v[140:143], v[46:47], off offset:448
	s_waitcnt vmcnt(10)
	v_pk_fma_f32 v[18:19], v[18:19], v[150:151], v[146:147]
	v_pk_fma_f32 v[16:17], v[16:17], v[148:149], v[144:145]
	s_waitcnt vmcnt(8)
	v_pk_fma_f32 v[10:11], v[10:11], v[216:217], v[154:155]
	v_pk_fma_f32 v[8:9], v[8:9], v[214:215], v[152:153]
	s_waitcnt vmcnt(6)
	v_pk_fma_f32 v[26:27], v[26:27], v[224:225], v[220:221]
	v_pk_fma_f32 v[24:25], v[24:25], v[222:223], v[218:219]
	s_waitcnt vmcnt(4)
	v_pk_fma_f32 v[14:15], v[14:15], v[232:233], v[228:229]
	v_pk_fma_f32 v[12:13], v[12:13], v[230:231], v[226:227]
	s_waitcnt vmcnt(2)
	v_pk_fma_f32 v[30:31], v[30:31], v[42:43], v[38:39]
	v_pk_fma_f32 v[28:29], v[28:29], v[40:41], v[36:37]
	s_waitcnt vmcnt(0)
	v_pk_fma_f32 v[34:35], v[34:35], v[142:143], v[138:139]
	v_pk_fma_f32 v[32:33], v[32:33], v[140:141], v[136:137]
	s_cbranch_scc0 .LBB0_380
	s_branch .LBB0_382
